# E_IN tiles remapped to XCD-owned row panels and post-phase row/V units permuted onto the XCD whose L2 holds their projection rows
# speedup vs baseline: 1.0822x; 1.0050x over previous
.LBB0_277:
	s_andn2_b64 vcc, exec, s[0:1]
	s_cbranch_vccnz .LBB0_354
	s_cmp_lg_u32 s27, 1
	s_mov_b64 s[0:1], -1
	s_cbranch_scc0 .LBB0_310
	s_load_dword s0, s[96:97], 0x0
	s_and_b32 s20, s74, 7
	s_waitcnt lgkmcnt(0)
	s_lshr_b32 s13, s0, 6
	v_cvt_f32_u32_e32 v0, s13
	s_sub_i32 s1, 0, s13
	s_add_i32 s0, s13, 27
	v_rcp_iflag_f32_e32 v0, v0
	s_nop 0
	v_mul_f32_e32 v0, 0x4f7ffffe, v0
	v_cvt_u32_f32_e32 v0, v0
	s_nop 0
	v_readfirstlane_b32 s8, v0
	s_mul_i32 s1, s1, s8
	s_mul_hi_u32 s1, s8, s1
	s_add_i32 s8, s8, s1
	s_mul_hi_u32 s1, s0, s8
	s_mul_i32 s8, s1, s13
	s_sub_i32 s0, s0, s8
	s_add_i32 s9, s1, 1
	s_sub_i32 s8, s0, s13
	s_cmp_ge_u32 s0, s13
	s_cselect_b32 s1, s9, s1
	s_cselect_b32 s0, s8, s0
	s_add_i32 s8, s1, 1
	s_cmp_ge_u32 s0, s13
	s_cselect_b32 s21, s8, s1
	s_mul_i32 s21, s21, 6
	s_cmp_ge_u32 s20, s21
	s_cbranch_scc1 .LBB0_309
	s_cmp_eq_u32 s13, 8
	s_cbranch_scc0 .Lin_orig1
	s_lshr_b32 s20, s74, 3
	s_movk_i32 s21, 0xa8
	s_mul_hi_u32 s9, s20, 0x2aaaaaab
	s_mul_i32 s11, s9, 6
	s_sub_i32 s11, s20, s11
	s_lshl_b32 s10, s11, 3
	s_and_b32 s11, s74, 7
	s_or_b32 s10, s10, s11
	s_lshl_b32 s10, s10, 7
	s_lshl_b32 s8, s9, 7
	s_add_i32 s20, s20, 64
	s_mov_b64 s[0:1], -1
	s_branch .LBB0_286
.Lin_orig1:
	s_lshl_b32 s0, s74, 4
	s_ashr_i32 s22, s74, 6
	s_and_b32 s23, s0, 0x380
	s_mov_b64 s[0:1], 0
	s_branch .LBB0_282

.LBB0_305:
	s_cmp_eq_u32 s13, 8
	s_cbranch_scc0 .Lin_orig2
	s_mul_hi_u32 s9, s20, 0x2aaaaaab
	s_mul_i32 s11, s9, 6
	s_sub_i32 s11, s20, s11
	s_lshl_b32 s48, s11, 3
	s_and_b32 s11, s74, 7
	s_or_b32 s48, s48, s11
	s_lshl_b32 s48, s48, 7
	s_lshl_b32 s43, s9, 7
	s_add_i32 s20, s20, 64
	s_mov_b64 s[14:15], -1
	s_mov_b64 s[0:1], -1
	s_branch .LBB0_290

.LBB0_310:
	s_andn2_b64 vcc, exec, s[0:1]
	s_cbranch_vccnz .LBB0_354
	s_cmpk_gt_i32 s74, 0x65f
	s_cbranch_scc1 .LBB0_354
	v_lshlrev_b32_e32 v2, 1, v124
	v_and_b32_e32 v3, 31, v124
	v_and_b32_e32 v0, 0x7e, v2
	v_lshlrev_b32_e32 v4, 1, v3
	s_lshl_b32 s13, s12, 8
	s_lshl_b32 s14, s12, 1
	v_and_b32_e32 v38, 30, v2
	s_waitcnt vmcnt(0)
	v_or_b32_e32 v34, 0x80, v0
	v_lshlrev_b32_e32 v2, 8, v124
	v_lshl_or_b32 v6, s12, 6, v4
	v_mov_b32_e32 v7, v117
	s_add_u32 s8, s2, 0xa2ce000
	v_readlane_b32 s48, v254, 46
	v_and_b32_e32 v36, 0x3000, v2
	v_lshlrev_b32_e32 v2, 7, v34
	v_or_b32_e32 v42, 0x100, v0
	s_addc_u32 s9, s3, 0
	v_lshlrev_b64 v[12:13], 2, v[6:7]
	v_readlane_b32 s49, v254, 47
	v_readlane_b32 s50, v254, 48
	v_readlane_b32 s51, v254, 49
	v_readlane_b32 s52, v254, 50
	v_readlane_b32 s53, v254, 51
	v_readlane_b32 s54, v254, 52
	v_readlane_b32 s55, v254, 53
	v_readlane_b32 s56, v254, 54
	v_readlane_b32 s57, v254, 55
	v_readlane_b32 s58, v254, 56
	v_readlane_b32 s59, v254, 57
	v_readlane_b32 s60, v254, 58
	v_readlane_b32 s61, v254, 59
	v_readlane_b32 s62, v254, 60
	v_readlane_b32 s63, v254, 61
	s_mul_i32 s30, s12, 0x600
	v_and_b32_e32 v40, 0x7000, v2
	v_or_b32_e32 v44, 0x180, v0
	v_lshlrev_b32_e32 v2, 7, v42
	s_add_u32 s10, s2, 0x4c000
	v_lshl_add_u64 v[6:7], s[58:59], 0, v[12:13]
	v_lshl_add_u64 v[8:9], s[60:61], 0, v[12:13]
	v_lshl_add_u64 v[10:11], s[62:63], 0, v[12:13]
	v_readlane_b32 s48, v255, 16
	v_and_b32_e32 v46, 0xb000, v2
	v_lshlrev_b32_e32 v2, 7, v44
	s_addc_u32 s11, s3, 0
	v_readlane_b32 s52, v255, 20
	s_lshl_b64 s[0:1], s[30:31], 2
	v_and_b32_e32 v48, 0xf000, v2
	v_ashrrev_i32_e32 v2, 2, v124
	v_readlane_b32 s53, v255, 21
	s_add_u32 s0, s52, s0
	v_cmp_gt_u32_e64 s[36:37], 16, v3
	v_and_b32_e32 v3, 8, v124
	v_and_b32_e32 v119, 0xffffffe0, v2
	v_and_b32_e32 v2, 64, v124
	v_lshlrev_b32_e32 v32, 2, v0
	v_mov_b32_e32 v33, v117
	s_addc_u32 s1, s53, s1
	v_cmp_eq_u32_e64 s[38:39], 0, v3
	v_cmp_eq_u32_e32 vcc, 0, v2
	v_mov_b32_e32 v2, 0xb00
	v_mov_b32_e32 v3, 0x500
	v_lshl_add_u64 v[14:15], s[0:1], 0, v[32:33]
	s_mov_b64 s[0:1], 0x1000
	v_cndmask_b32_e32 v116, v2, v3, vcc
	v_mov_b32_e32 v2, 0x13fce000
	v_mov_b32_e32 v3, 0x13cce000
	v_lshl_add_u64 v[16:17], v[14:15], 0, s[0:1]
	s_mov_b64 s[0:1], 0x1200
	v_cndmask_b32_e32 v26, v2, v3, vcc
	v_mov_b32_e32 v2, 0x3000000
	v_bfrev_b32_e32 v3, 64
	v_lshl_add_u64 v[18:19], v[14:15], 0, s[0:1]
	s_mov_b64 s[0:1], 0x1400
	v_cndmask_b32_e32 v30, v2, v3, vcc
	v_mov_b32_e32 v31, v117
	v_mov_b32_e32 v2, 0x13bce000
	v_mov_b32_e32 v3, 0x13ace000
	v_lshlrev_b32_e32 v24, 1, v0
	v_mov_b32_e32 v25, v117
	v_lshl_add_u64 v[20:21], v[14:15], 0, s[0:1]
	s_mov_b64 s[0:1], 0x1600
	v_and_b32_e32 v35, 14, v4
	v_mov_b32_e32 v27, v117
	v_cndmask_b32_e32 v28, v2, v3, vcc
	v_mov_b32_e32 v29, v117
	v_lshl_add_u64 v[2:3], s[2:3], 0, v[24:25]
	v_readlane_b32 s49, v255, 17
	v_lshl_add_u64 v[22:23], v[14:15], 0, s[0:1]
	v_lshl_add_u64 v[50:51], s[8:9], 0, v[116:117]
	v_lshl_add_u64 v[30:31], s[46:47], 0, v[30:31]
	s_mov_b64 s[0:1], 0x142ce000
	s_waitcnt lgkmcnt(0)
	v_add_u32_e32 v1, 0xfffffe80, v126
	v_or_b32_e32 v121, s13, v0
	v_lshl_add_u64 v[4:5], s[46:47], 0, v[32:33]
	v_lshl_add_u64 v[12:13], s[48:49], 0, v[12:13]
	v_lshl_add_u64 v[24:25], v[50:51], 0, v[24:25]
	v_lshl_add_u64 v[26:27], s[2:3], 0, v[26:27]
	v_lshl_add_u64 v[28:29], s[2:3], 0, v[28:29]
	v_lshl_add_u64 v[30:31], v[30:31], 0, v[32:33]
	v_lshl_add_u64 v[32:33], v[2:3], 0, s[0:1]
	v_lshlrev_b32_e32 v122, 2, v35
	v_lshlrev_b32_e32 v34, 1, v34
	v_lshlrev_b32_e32 v36, 1, v36
	v_lshlrev_b32_e32 v38, 1, v38
	v_lshlrev_b32_e32 v40, 1, v40
	v_lshlrev_b32_e32 v42, 1, v42
	v_lshlrev_b32_e32 v44, 1, v44
	v_lshlrev_b32_e32 v46, 1, v46
	v_lshlrev_b32_e32 v48, 1, v48
	s_mov_b32 s99, s74
	v_readlane_b32 s50, v255, 18
	v_readlane_b32 s51, v255, 19
	v_readlane_b32 s54, v255, 22
	v_readlane_b32 s55, v255, 23
	v_readlane_b32 s56, v255, 24
	v_readlane_b32 s57, v255, 25
	v_readlane_b32 s58, v255, 26
	v_readlane_b32 s59, v255, 27
	v_readlane_b32 s60, v255, 28
	v_readlane_b32 s61, v255, 29
	v_readlane_b32 s62, v255, 30
	v_readlane_b32 s63, v255, 31
	s_branch .LBB0_315

.LBB0_314:
	s_load_dword s0, s[96:97], 0x0
	s_waitcnt lgkmcnt(0)
	s_add_i32 s99, s0, s99
	s_cmpk_gt_i32 s99, 0x65f
	s_cbranch_scc1 .LBB0_354
.LBB0_315:
	s_cmpk_gt_i32 s99, 0x5f
	s_cbranch_scc1 .Lp2_row
	s_and_b32 s0, s99, 7
	s_lshr_b32 s1, s99, 3
	s_lshr_b32 s98, s1, 1
	s_lshl_b32 s98, s98, 3
	s_or_b32 s98, s98, s0
	s_lshl_b32 s98, s98, 1
	s_and_b32 s1, s1, 1
	s_or_b32 s15, s98, s1
	s_branch .Lp2_done
.Lp2_row:
	s_add_i32 s1, s99, 0xffffffa0
	s_and_b32 s0, s1, 7
	s_lshr_b32 s1, s1, 3
	s_lshr_b32 s98, s1, 5
	s_lshl_b32 s98, s98, 3
	s_or_b32 s98, s98, s0
	s_lshl_b32 s98, s98, 5
	s_and_b32 s1, s1, 31
	s_or_b32 s98, s98, s1
	s_add_i32 s15, s98, 0x60

.Lh_n5:
	s_cmp_eq_u32 s27, 0
	s_cbranch_scc0 .Lh_n0
	s_lshr_b32 s98, s74, 3
	s_cmp_lt_u32 s98, 40
	s_cbranch_scc1 .Lh_norm
	s_mov_b32 s10, 1
	s_mov_b32 s99, 3
	s_branch .LBB0_365
